# mode6 skip-empty-cand + FoX: QK LDS reads hoisted, canonicalizing v_max removed
# speedup vs baseline: 1.0776x; 1.0085x over previous
;     ...
; #pragma unroll 1
;     for (int it = 0; it < nit; ++it) {
;         const int kt = kt0 + 4 * (it >> 1), kb = it & 1;
;         const int itn = it + 1 < nit ? it + 1 : it;
;         const bf16_t* np = ikp + (size_t)(256 * (itn >> 1) + 32 * (itn & 1)) * NZ; const bf16x8 n0 = *(const bf16x8*)np, n1 = *(const bf16x8*)(np + 16);
;         f32x2v sc2[8];
; #pragma unroll
;         for (int r = 0; r < 8; ++r) sc2[r] = (f32x2v){0.f, 0.f};
;     ...
;         { f32x16 zero16;
; #pragma unroll
;           for (int r = 0; r < 16; ++r) zero16[r] = 0.f;
;           f32x16 dA0, dA1, dB0, dB1; float wA0, wA1, wB0, wB1;
;           SW_MF(0, dA0, dA1, wA0, wA1);
;           SW_MF(1, dB0, dB1, wB0, wB1); __builtin_amdgcn_sched_barrier(0);
;           SW_VA(dA0, dA1, wA0, wA1);    __builtin_amdgcn_sched_barrier(0);
;           SW_MF(2, dA0, dA1, wA0, wA1); __builtin_amdgcn_sched_barrier(0);
;           SW_VA(dB0, dB1, wB0, wB1);    __builtin_amdgcn_sched_barrier(0);
;           SW_MF(3, dB0, dB1, wB0, wB1); __builtin_amdgcn_sched_barrier(0);
;           SW_VA(dA0, dA1, wA0, wA1);    __builtin_amdgcn_sched_barrier(0);
;           SW_VA(dB0, dB1, wB0, wB1); }
.Lm6_loop:
	s_add_i32 s1, s18, 1
	s_cmp_lt_u32 s1, s25
	s_cselect_b32 s3, s1, s18
	s_lshl_b32 vcc_lo, s3, 7
	s_and_b32 vcc_lo, vcc_lo, 0x7fffff00
	s_lshl_b32 s3, s3, 5
	s_and_b32 s3, s3, 32
	s_or_b32 s3, vcc_lo, s3
	s_lshr_b32 s0, s18, 1
	s_lshl_b32 s0, s0, 2
	s_add_i32 s0, s0, s24
	s_lshl_b32 s0, s0, 6
	s_and_b32 s2, s18, 1
	s_lshl_b32 s2, s2, 5
	s_or_b32 s0, s0, s2
	ds_read_b128 v[0:3], v165
	ds_read_b128 v[4:7], v165 offset:32
	ds_read_b128 v[8:11], v165 offset:64
	ds_read_b128 v[12:15], v165 offset:96
	ds_read2st64_b32 v[80:81], v167 offset1:1
	ds_read2st64_b32 v[82:83], v167 offset0:2 offset1:3
	ds_read2st64_b32 v[84:85], v167 offset0:4 offset1:5
	ds_read2st64_b32 v[86:87], v167 offset0:6 offset1:7
	v_mad_u64_u32 v[114:115], vcc, s3, v223, v[140:141]
	v_or_b32_e32 v124, s0, v159
	global_load_dwordx4 v[64:67], v[114:115], off
	global_load_dwordx4 v[68:71], v[114:115], off offset:32
	s_waitcnt vmcnt(2) lgkmcnt(6)
	v_mfma_f32_32x32x16_bf16 v[16:31], v[132:135], v[0:3], 0
	v_mfma_f32_32x32x16_bf16 v[16:31], v[128:131], v[4:7], v[16:31]
	ds_read_b128 v[0:3], v165 offset:128
	ds_read_b128 v[4:7], v165 offset:160
	s_waitcnt lgkmcnt(6)
	v_mfma_f32_32x32x16_bf16 v[32:47], v[132:135], v[8:11], 0
	v_mfma_f32_32x32x16_bf16 v[32:47], v[128:131], v[12:15], v[32:47]
	ds_read_b128 v[8:11], v165 offset:192
	ds_read_b128 v[12:15], v165 offset:224
	s_nop 7
	s_waitcnt lgkmcnt(4)
	v_mov_b32_e32 v104, v81
	v_mov_b32_e32 v106, v83
	v_mov_b32_e32 v108, v85
	v_mov_b32_e32 v110, v87
	v_pk_mul_f32 v[16:17], v[16:17], v[112:113] clamp
	v_pk_mul_f32 v[18:19], v[18:19], v[112:113] clamp
	v_pk_mul_f32 v[20:21], v[20:21], v[112:113] clamp
	v_pk_mul_f32 v[22:23], v[22:23], v[112:113] clamp
	v_pk_mul_f32 v[24:25], v[24:25], v[112:113] clamp
	v_pk_mul_f32 v[26:27], v[26:27], v[112:113] clamp
	v_pk_mul_f32 v[28:29], v[28:29], v[112:113] clamp
	v_pk_mul_f32 v[30:31], v[30:31], v[112:113] clamp
	v_pk_fma_f32 v[88:89], v[16:17], v[80:81], 0 op_sel_hi:[1,0,0]
	v_pk_fma_f32 v[90:91], v[18:19], v[80:81], 0 op_sel_hi:[1,0,0]
	v_pk_fma_f32 v[92:93], v[20:21], v[80:81], 0 op_sel_hi:[1,0,0]
	v_pk_fma_f32 v[94:95], v[22:23], v[80:81], 0 op_sel_hi:[1,0,0]
	v_pk_fma_f32 v[96:97], v[24:25], v[80:81], 0 op_sel_hi:[1,0,0]
	v_pk_fma_f32 v[98:99], v[26:27], v[80:81], 0 op_sel_hi:[1,0,0]
	v_pk_fma_f32 v[100:101], v[28:29], v[80:81], 0 op_sel_hi:[1,0,0]
	v_pk_fma_f32 v[102:103], v[30:31], v[80:81], 0 op_sel_hi:[1,0,0]
	s_waitcnt lgkmcnt(2)
	v_mfma_f32_32x32x16_bf16 v[16:31], v[132:135], v[0:3], 0
	v_mfma_f32_32x32x16_bf16 v[16:31], v[128:131], v[4:7], v[16:31]
	ds_read_b128 v[0:3], v165 offset:256
	ds_read_b128 v[4:7], v165 offset:288
	v_pk_mul_f32 v[32:33], v[32:33], v[112:113] clamp
	v_pk_mul_f32 v[34:35], v[34:35], v[112:113] clamp
	v_pk_mul_f32 v[36:37], v[36:37], v[112:113] clamp
	v_pk_mul_f32 v[38:39], v[38:39], v[112:113] clamp
	v_pk_mul_f32 v[40:41], v[40:41], v[112:113] clamp
	v_pk_mul_f32 v[42:43], v[42:43], v[112:113] clamp
	v_pk_mul_f32 v[44:45], v[44:45], v[112:113] clamp
	v_pk_mul_f32 v[46:47], v[46:47], v[112:113] clamp
	v_pk_fma_f32 v[88:89], v[32:33], v[104:105], v[88:89] op_sel_hi:[1,0,1]
	v_pk_fma_f32 v[90:91], v[34:35], v[104:105], v[90:91] op_sel_hi:[1,0,1]
	v_pk_fma_f32 v[92:93], v[36:37], v[104:105], v[92:93] op_sel_hi:[1,0,1]
	v_pk_fma_f32 v[94:95], v[38:39], v[104:105], v[94:95] op_sel_hi:[1,0,1]
	v_pk_fma_f32 v[96:97], v[40:41], v[104:105], v[96:97] op_sel_hi:[1,0,1]
	v_pk_fma_f32 v[98:99], v[42:43], v[104:105], v[98:99] op_sel_hi:[1,0,1]
	v_pk_fma_f32 v[100:101], v[44:45], v[104:105], v[100:101] op_sel_hi:[1,0,1]
	v_pk_fma_f32 v[102:103], v[46:47], v[104:105], v[102:103] op_sel_hi:[1,0,1]
	s_waitcnt lgkmcnt(2)
	v_mfma_f32_32x32x16_bf16 v[32:47], v[132:135], v[8:11], 0
	v_mfma_f32_32x32x16_bf16 v[32:47], v[128:131], v[12:15], v[32:47]
	ds_read_b128 v[8:11], v165 offset:320
	ds_read_b128 v[12:15], v165 offset:352
	v_pk_mul_f32 v[16:17], v[16:17], v[112:113] clamp
	v_pk_mul_f32 v[18:19], v[18:19], v[112:113] clamp
	v_pk_mul_f32 v[20:21], v[20:21], v[112:113] clamp
	v_pk_mul_f32 v[22:23], v[22:23], v[112:113] clamp
	v_pk_mul_f32 v[24:25], v[24:25], v[112:113] clamp
	v_pk_mul_f32 v[26:27], v[26:27], v[112:113] clamp
	v_pk_mul_f32 v[28:29], v[28:29], v[112:113] clamp
	v_pk_mul_f32 v[30:31], v[30:31], v[112:113] clamp
	v_pk_fma_f32 v[88:89], v[16:17], v[82:83], v[88:89] op_sel_hi:[1,0,1]
	v_pk_fma_f32 v[90:91], v[18:19], v[82:83], v[90:91] op_sel_hi:[1,0,1]
	v_pk_fma_f32 v[92:93], v[20:21], v[82:83], v[92:93] op_sel_hi:[1,0,1]
	v_pk_fma_f32 v[94:95], v[22:23], v[82:83], v[94:95] op_sel_hi:[1,0,1]
	v_pk_fma_f32 v[96:97], v[24:25], v[82:83], v[96:97] op_sel_hi:[1,0,1]
	v_pk_fma_f32 v[98:99], v[26:27], v[82:83], v[98:99] op_sel_hi:[1,0,1]
	v_pk_fma_f32 v[100:101], v[28:29], v[82:83], v[100:101] op_sel_hi:[1,0,1]
	v_pk_fma_f32 v[102:103], v[30:31], v[82:83], v[102:103] op_sel_hi:[1,0,1]
	s_waitcnt lgkmcnt(2)
	v_mfma_f32_32x32x16_bf16 v[16:31], v[132:135], v[0:3], 0
	v_mfma_f32_32x32x16_bf16 v[16:31], v[128:131], v[4:7], v[16:31]
	ds_read_b128 v[0:3], v165 offset:384
	ds_read_b128 v[4:7], v165 offset:416
	v_pk_mul_f32 v[32:33], v[32:33], v[112:113] clamp
	v_pk_mul_f32 v[34:35], v[34:35], v[112:113] clamp
	v_pk_mul_f32 v[36:37], v[36:37], v[112:113] clamp
	v_pk_mul_f32 v[38:39], v[38:39], v[112:113] clamp
	v_pk_mul_f32 v[40:41], v[40:41], v[112:113] clamp
	v_pk_mul_f32 v[42:43], v[42:43], v[112:113] clamp
	v_pk_mul_f32 v[44:45], v[44:45], v[112:113] clamp
	v_pk_mul_f32 v[46:47], v[46:47], v[112:113] clamp
	v_pk_fma_f32 v[88:89], v[32:33], v[106:107], v[88:89] op_sel_hi:[1,0,1]
	v_pk_fma_f32 v[90:91], v[34:35], v[106:107], v[90:91] op_sel_hi:[1,0,1]
	v_pk_fma_f32 v[92:93], v[36:37], v[106:107], v[92:93] op_sel_hi:[1,0,1]
	v_pk_fma_f32 v[94:95], v[38:39], v[106:107], v[94:95] op_sel_hi:[1,0,1]
	v_pk_fma_f32 v[96:97], v[40:41], v[106:107], v[96:97] op_sel_hi:[1,0,1]
	v_pk_fma_f32 v[98:99], v[42:43], v[106:107], v[98:99] op_sel_hi:[1,0,1]
	v_pk_fma_f32 v[100:101], v[44:45], v[106:107], v[100:101] op_sel_hi:[1,0,1]
	v_pk_fma_f32 v[102:103], v[46:47], v[106:107], v[102:103] op_sel_hi:[1,0,1]
	s_waitcnt lgkmcnt(2)
; __device__ __forceinline__ unsigned sortable(float f) { const unsigned u = __float_as_uint(f); return u ^ ((unsigned)((int)u >> 31) | 0x80000000u); }
; __device__ __forceinline__ int bucketf(float f) { const unsigned u = __float_as_uint(f); const int idx = (int)((u >> 20) & 0x7FFu); const int c = min(max(idx - 816, 128), 255); return c ^ (((int)u >> 31) & 255); }
;     ...
;         { f32x16 zero16;
; #pragma unroll
;           for (int r = 0; r < 16; ++r) zero16[r] = 0.f;
;           f32x16 dA0, dA1, dB0, dB1; float wA0, wA1, wB0, wB1;
;           SW_MF(0, dA0, dA1, wA0, wA1);
;           SW_MF(1, dB0, dB1, wB0, wB1); __builtin_amdgcn_sched_barrier(0);
;           SW_VA(dA0, dA1, wA0, wA1);    __builtin_amdgcn_sched_barrier(0);
;           SW_MF(2, dA0, dA1, wA0, wA1); __builtin_amdgcn_sched_barrier(0);
;           SW_VA(dB0, dB1, wB0, wB1);    __builtin_amdgcn_sched_barrier(0);
;           SW_MF(3, dB0, dB1, wB0, wB1); __builtin_amdgcn_sched_barrier(0);
;           SW_VA(dA0, dA1, wA0, wA1);    __builtin_amdgcn_sched_barrier(0);
;           SW_VA(dB0, dB1, wB0, wB1); }
;     ...
;         f32x16 sc;
; #pragma unroll
;         for (int r = 0; r < 16; ++r) sc[r] = sc2[r >> 1][r & 1];
;         const unsigned s0 = (unsigned)(64 * kt + 32 * kb + 4 * hi);
; #pragma unroll
;         for (int r = 0; r < 16; ++r) { const unsigned s = s0 + (unsigned)((r & 3) + 8 * (r >> 2));
;             if (MODE == 5) { __hip_atomic_fetch_add(hist + 64 * bucketf(sc[r]), 1u, __ATOMIC_RELAXED, __HIP_MEMORY_SCOPE_WORKGROUP); continue; }
;             if (MODE == 6) {
;                 if (sc[r] >= t_hi) { const unsigned pos = __hip_atomic_fetch_add(cnt, 1u, __ATOMIC_RELAXED, __HIP_MEMORY_SCOPE_WORKGROUP); sel[pos & 255u] = (unsigned short)s; }
;                 else if (sc[r] >= t_lo) { const unsigned key = (sortable(sc[r]) & 0xFFFFE000u) | (8191u - s);
;                     const unsigned pos = __hip_atomic_fetch_add(ccnt, 1u, __ATOMIC_RELAXED, __HIP_MEMORY_SCOPE_WORKGROUP); cand[pos & (DS_CAP - 1)] = key; }
	v_mfma_f32_32x32x16_bf16 v[32:47], v[132:135], v[8:11], 0
	v_mfma_f32_32x32x16_bf16 v[32:47], v[128:131], v[12:15], v[32:47]
	ds_read_b128 v[8:11], v165 offset:448
	ds_read_b128 v[12:15], v165 offset:480
	v_pk_mul_f32 v[16:17], v[16:17], v[112:113] clamp
	v_pk_mul_f32 v[18:19], v[18:19], v[112:113] clamp
	v_pk_mul_f32 v[20:21], v[20:21], v[112:113] clamp
	v_pk_mul_f32 v[22:23], v[22:23], v[112:113] clamp
	v_pk_mul_f32 v[24:25], v[24:25], v[112:113] clamp
	v_pk_mul_f32 v[26:27], v[26:27], v[112:113] clamp
	v_pk_mul_f32 v[28:29], v[28:29], v[112:113] clamp
	v_pk_mul_f32 v[30:31], v[30:31], v[112:113] clamp
	v_pk_fma_f32 v[88:89], v[16:17], v[84:85], v[88:89] op_sel_hi:[1,0,1]
	v_pk_fma_f32 v[90:91], v[18:19], v[84:85], v[90:91] op_sel_hi:[1,0,1]
	v_pk_fma_f32 v[92:93], v[20:21], v[84:85], v[92:93] op_sel_hi:[1,0,1]
	v_pk_fma_f32 v[94:95], v[22:23], v[84:85], v[94:95] op_sel_hi:[1,0,1]
	v_pk_fma_f32 v[96:97], v[24:25], v[84:85], v[96:97] op_sel_hi:[1,0,1]
	v_pk_fma_f32 v[98:99], v[26:27], v[84:85], v[98:99] op_sel_hi:[1,0,1]
	v_pk_fma_f32 v[100:101], v[28:29], v[84:85], v[100:101] op_sel_hi:[1,0,1]
	v_pk_fma_f32 v[102:103], v[30:31], v[84:85], v[102:103] op_sel_hi:[1,0,1]
	s_waitcnt lgkmcnt(2)
	v_mfma_f32_32x32x16_bf16 v[16:31], v[132:135], v[0:3], 0
	v_mfma_f32_32x32x16_bf16 v[16:31], v[128:131], v[4:7], v[16:31]
	v_pk_mul_f32 v[32:33], v[32:33], v[112:113] clamp
	v_pk_mul_f32 v[34:35], v[34:35], v[112:113] clamp
	v_pk_mul_f32 v[36:37], v[36:37], v[112:113] clamp
	v_pk_mul_f32 v[38:39], v[38:39], v[112:113] clamp
	v_pk_mul_f32 v[40:41], v[40:41], v[112:113] clamp
	v_pk_mul_f32 v[42:43], v[42:43], v[112:113] clamp
	v_pk_mul_f32 v[44:45], v[44:45], v[112:113] clamp
	v_pk_mul_f32 v[46:47], v[46:47], v[112:113] clamp
	v_pk_fma_f32 v[88:89], v[32:33], v[108:109], v[88:89] op_sel_hi:[1,0,1]
	v_pk_fma_f32 v[90:91], v[34:35], v[108:109], v[90:91] op_sel_hi:[1,0,1]
	v_pk_fma_f32 v[92:93], v[36:37], v[108:109], v[92:93] op_sel_hi:[1,0,1]
	v_pk_fma_f32 v[94:95], v[38:39], v[108:109], v[94:95] op_sel_hi:[1,0,1]
	v_pk_fma_f32 v[96:97], v[40:41], v[108:109], v[96:97] op_sel_hi:[1,0,1]
	v_pk_fma_f32 v[98:99], v[42:43], v[108:109], v[98:99] op_sel_hi:[1,0,1]
	v_pk_fma_f32 v[100:101], v[44:45], v[108:109], v[100:101] op_sel_hi:[1,0,1]
	v_pk_fma_f32 v[102:103], v[46:47], v[108:109], v[102:103] op_sel_hi:[1,0,1]
	s_waitcnt lgkmcnt(0)
	v_mfma_f32_32x32x16_bf16 v[32:47], v[132:135], v[8:11], 0
	v_mfma_f32_32x32x16_bf16 v[32:47], v[128:131], v[12:15], v[32:47]
	v_pk_mul_f32 v[16:17], v[16:17], v[112:113] clamp
	v_pk_mul_f32 v[18:19], v[18:19], v[112:113] clamp
	v_pk_mul_f32 v[20:21], v[20:21], v[112:113] clamp
	v_pk_mul_f32 v[22:23], v[22:23], v[112:113] clamp
	v_pk_mul_f32 v[24:25], v[24:25], v[112:113] clamp
	v_pk_mul_f32 v[26:27], v[26:27], v[112:113] clamp
	v_pk_mul_f32 v[28:29], v[28:29], v[112:113] clamp
	v_pk_mul_f32 v[30:31], v[30:31], v[112:113] clamp
	v_pk_fma_f32 v[88:89], v[16:17], v[86:87], v[88:89] op_sel_hi:[1,0,1]
	v_pk_fma_f32 v[90:91], v[18:19], v[86:87], v[90:91] op_sel_hi:[1,0,1]
	v_pk_fma_f32 v[92:93], v[20:21], v[86:87], v[92:93] op_sel_hi:[1,0,1]
	v_pk_fma_f32 v[94:95], v[22:23], v[86:87], v[94:95] op_sel_hi:[1,0,1]
	v_pk_fma_f32 v[96:97], v[24:25], v[86:87], v[96:97] op_sel_hi:[1,0,1]
	v_pk_fma_f32 v[98:99], v[26:27], v[86:87], v[98:99] op_sel_hi:[1,0,1]
	v_pk_fma_f32 v[100:101], v[28:29], v[86:87], v[100:101] op_sel_hi:[1,0,1]
	v_pk_fma_f32 v[102:103], v[30:31], v[86:87], v[102:103] op_sel_hi:[1,0,1]
	v_pk_mul_f32 v[32:33], v[32:33], v[112:113] clamp
	v_pk_mul_f32 v[34:35], v[34:35], v[112:113] clamp
	v_pk_mul_f32 v[36:37], v[36:37], v[112:113] clamp
	v_pk_mul_f32 v[38:39], v[38:39], v[112:113] clamp
	v_pk_mul_f32 v[40:41], v[40:41], v[112:113] clamp
	v_pk_mul_f32 v[42:43], v[42:43], v[112:113] clamp
	v_pk_mul_f32 v[44:45], v[44:45], v[112:113] clamp
	v_pk_mul_f32 v[46:47], v[46:47], v[112:113] clamp
	v_pk_fma_f32 v[88:89], v[32:33], v[110:111], v[88:89] op_sel_hi:[1,0,1]
	v_pk_fma_f32 v[90:91], v[34:35], v[110:111], v[90:91] op_sel_hi:[1,0,1]
	v_pk_fma_f32 v[92:93], v[36:37], v[110:111], v[92:93] op_sel_hi:[1,0,1]
	v_pk_fma_f32 v[94:95], v[38:39], v[110:111], v[94:95] op_sel_hi:[1,0,1]
	v_pk_fma_f32 v[96:97], v[40:41], v[110:111], v[96:97] op_sel_hi:[1,0,1]
	v_pk_fma_f32 v[98:99], v[42:43], v[110:111], v[98:99] op_sel_hi:[1,0,1]
	v_pk_fma_f32 v[100:101], v[44:45], v[110:111], v[100:101] op_sel_hi:[1,0,1]
	v_pk_fma_f32 v[102:103], v[46:47], v[110:111], v[102:103] op_sel_hi:[1,0,1]
	v_cmp_ge_f32_e64 s[40:41], v88, v122
	v_cmp_ge_f32_e64 s[42:43], v88, v123
	v_mov_b32_e32 v18, v124
	s_andn2_b64 s[42:43], s[42:43], s[40:41]
	s_mov_b64 exec, s[40:41]
	ds_add_rtn_u32 v16, v180, v222
	s_mov_b64 exec, s[42:43]
	ds_add_rtn_u32 v16, v171, v222
	s_mov_b64 exec, -1
	v_cmp_ge_f32_e64 s[44:45], v89, v122
	v_cmp_ge_f32_e64 s[22:23], v89, v123
	v_or_b32_e32 v19, 1, v124
	s_andn2_b64 s[22:23], s[22:23], s[44:45]
	s_mov_b64 exec, s[44:45]
	ds_add_rtn_u32 v17, v180, v222
	s_mov_b64 exec, s[22:23]
	ds_add_rtn_u32 v17, v171, v222
	s_mov_b64 exec, -1
	s_waitcnt lgkmcnt(2)
	v_and_b32_e32 v16, 0xff, v16
	s_mov_b64 exec, s[40:41]
	v_lshl_add_u32 v20, v16, 1, v179
	ds_write_b16 v20, v18
	s_mov_b64 exec, s[42:43]
	s_cbranch_execz .Lm6_nb0
	v_ashrrev_i32_e32 v22, 31, v88
	v_sub_u32_e32 v18, 0x1fff, v18
	v_lshl_add_u32 v20, v16, 2, v169
	v_bitop3_b32 v21, v22, v88, s64 bitop3:0x36
	v_and_or_b32 v21, v21, s65, v18
	ds_write_b32 v20, v21
; __device__ __forceinline__ unsigned sortable(float f) { const unsigned u = __float_as_uint(f); return u ^ ((unsigned)((int)u >> 31) | 0x80000000u); }
; __device__ __forceinline__ int bucketf(float f) { const unsigned u = __float_as_uint(f); const int idx = (int)((u >> 20) & 0x7FFu); const int c = min(max(idx - 816, 128), 255); return c ^ (((int)u >> 31) & 255); }
;     ...
;         const unsigned s0 = (unsigned)(64 * kt + 32 * kb + 4 * hi);
; #pragma unroll
;         for (int r = 0; r < 16; ++r) { const unsigned s = s0 + (unsigned)((r & 3) + 8 * (r >> 2));
;             if (MODE == 5) { __hip_atomic_fetch_add(hist + 64 * bucketf(sc[r]), 1u, __ATOMIC_RELAXED, __HIP_MEMORY_SCOPE_WORKGROUP); continue; }
;             if (MODE == 6) {
;                 if (sc[r] >= t_hi) { const unsigned pos = __hip_atomic_fetch_add(cnt, 1u, __ATOMIC_RELAXED, __HIP_MEMORY_SCOPE_WORKGROUP); sel[pos & 255u] = (unsigned short)s; }
;                 else if (sc[r] >= t_lo) { const unsigned key = (sortable(sc[r]) & 0xFFFFE000u) | (8191u - s);
;                     const unsigned pos = __hip_atomic_fetch_add(ccnt, 1u, __ATOMIC_RELAXED, __HIP_MEMORY_SCOPE_WORKGROUP); cand[pos & (DS_CAP - 1)] = key; }
;                 continue; }
.Lm6_nb0:
	s_mov_b64 exec, -1
	v_cmp_ge_f32_e64 s[40:41], v90, v122
	v_cmp_ge_f32_e64 s[42:43], v90, v123
	v_or_b32_e32 v18, 2, v124
	s_andn2_b64 s[42:43], s[42:43], s[40:41]
	s_mov_b64 exec, s[40:41]
	ds_add_rtn_u32 v16, v180, v222
	s_mov_b64 exec, s[42:43]
	ds_add_rtn_u32 v16, v171, v222
	s_mov_b64 exec, -1
	s_waitcnt lgkmcnt(3)
	v_and_b32_e32 v17, 0xff, v17
	s_mov_b64 exec, s[44:45]
	v_lshl_add_u32 v20, v17, 1, v179
	ds_write_b16 v20, v19
	s_mov_b64 exec, s[22:23]
	s_cbranch_execz .Lm6_nb1
	v_ashrrev_i32_e32 v22, 31, v89
	v_sub_u32_e32 v19, 0x1fff, v19
	v_lshl_add_u32 v20, v17, 2, v169
	v_bitop3_b32 v21, v22, v89, s64 bitop3:0x36
	v_and_or_b32 v21, v21, s65, v19
	ds_write_b32 v20, v21
.Lm6_nb1:
	s_mov_b64 exec, -1
	v_cmp_ge_f32_e64 s[44:45], v91, v122
	v_cmp_ge_f32_e64 s[22:23], v91, v123
	v_or_b32_e32 v19, 3, v124
	s_andn2_b64 s[22:23], s[22:23], s[44:45]
	s_mov_b64 exec, s[44:45]
	ds_add_rtn_u32 v17, v180, v222
	s_mov_b64 exec, s[22:23]
	ds_add_rtn_u32 v17, v171, v222
	s_mov_b64 exec, -1
	s_waitcnt lgkmcnt(3)
	v_and_b32_e32 v16, 0xff, v16
	s_mov_b64 exec, s[40:41]
	v_lshl_add_u32 v20, v16, 1, v179
	ds_write_b16 v20, v18
	s_mov_b64 exec, s[42:43]
	s_cbranch_execz .Lm6_nb2
	v_ashrrev_i32_e32 v22, 31, v90
	v_sub_u32_e32 v18, 0x1fff, v18
	v_lshl_add_u32 v20, v16, 2, v169
	v_bitop3_b32 v21, v22, v90, s64 bitop3:0x36
	v_and_or_b32 v21, v21, s65, v18
	ds_write_b32 v20, v21
.Lm6_nb2:
	s_mov_b64 exec, -1
	v_cmp_ge_f32_e64 s[40:41], v92, v122
	v_cmp_ge_f32_e64 s[42:43], v92, v123
	v_or_b32_e32 v18, 8, v124
	s_andn2_b64 s[42:43], s[42:43], s[40:41]
	s_mov_b64 exec, s[40:41]
	ds_add_rtn_u32 v16, v180, v222
	s_mov_b64 exec, s[42:43]
	ds_add_rtn_u32 v16, v171, v222
	s_mov_b64 exec, -1
	s_waitcnt lgkmcnt(3)
	v_and_b32_e32 v17, 0xff, v17
	s_mov_b64 exec, s[44:45]
	v_lshl_add_u32 v20, v17, 1, v179
	ds_write_b16 v20, v19
	s_mov_b64 exec, s[22:23]
	s_cbranch_execz .Lm6_nb3
	v_ashrrev_i32_e32 v22, 31, v91
	v_sub_u32_e32 v19, 0x1fff, v19
	v_lshl_add_u32 v20, v17, 2, v169
	v_bitop3_b32 v21, v22, v91, s64 bitop3:0x36
	v_and_or_b32 v21, v21, s65, v19
	ds_write_b32 v20, v21
.Lm6_nb3:
	s_mov_b64 exec, -1
	v_cmp_ge_f32_e64 s[44:45], v93, v122
	v_cmp_ge_f32_e64 s[22:23], v93, v123
	v_or_b32_e32 v19, 9, v124
	s_andn2_b64 s[22:23], s[22:23], s[44:45]
	s_mov_b64 exec, s[44:45]
	ds_add_rtn_u32 v17, v180, v222
	s_mov_b64 exec, s[22:23]
	ds_add_rtn_u32 v17, v171, v222
	s_mov_b64 exec, -1
	s_waitcnt lgkmcnt(3)
	v_and_b32_e32 v16, 0xff, v16
	s_mov_b64 exec, s[40:41]
	v_lshl_add_u32 v20, v16, 1, v179
	ds_write_b16 v20, v18
	s_mov_b64 exec, s[42:43]
	s_cbranch_execz .Lm6_nb4
	v_ashrrev_i32_e32 v22, 31, v92
	v_sub_u32_e32 v18, 0x1fff, v18
	v_lshl_add_u32 v20, v16, 2, v169
	v_bitop3_b32 v21, v22, v92, s64 bitop3:0x36
	v_and_or_b32 v21, v21, s65, v18
	ds_write_b32 v20, v21
.Lm6_nb4:
	s_mov_b64 exec, -1
	v_cmp_ge_f32_e64 s[40:41], v94, v122
	v_cmp_ge_f32_e64 s[42:43], v94, v123
	v_or_b32_e32 v18, 10, v124
	s_andn2_b64 s[42:43], s[42:43], s[40:41]
	s_mov_b64 exec, s[40:41]
	ds_add_rtn_u32 v16, v180, v222
	s_mov_b64 exec, s[42:43]
	ds_add_rtn_u32 v16, v171, v222
	s_mov_b64 exec, -1
	s_waitcnt lgkmcnt(3)
	v_and_b32_e32 v17, 0xff, v17
	s_mov_b64 exec, s[44:45]
	v_lshl_add_u32 v20, v17, 1, v179
	ds_write_b16 v20, v19
	s_mov_b64 exec, s[22:23]
	s_cbranch_execz .Lm6_nb5
	v_ashrrev_i32_e32 v22, 31, v93
	v_sub_u32_e32 v19, 0x1fff, v19
	v_lshl_add_u32 v20, v17, 2, v169
	v_bitop3_b32 v21, v22, v93, s64 bitop3:0x36
	v_and_or_b32 v21, v21, s65, v19
	ds_write_b32 v20, v21
.Lm6_nb5:
	s_mov_b64 exec, -1
	v_cmp_ge_f32_e64 s[44:45], v95, v122
	v_cmp_ge_f32_e64 s[22:23], v95, v123
	v_or_b32_e32 v19, 11, v124
	s_andn2_b64 s[22:23], s[22:23], s[44:45]
	s_mov_b64 exec, s[44:45]
	ds_add_rtn_u32 v17, v180, v222
	s_mov_b64 exec, s[22:23]
	ds_add_rtn_u32 v17, v171, v222
	s_mov_b64 exec, -1
	s_waitcnt lgkmcnt(3)
	v_and_b32_e32 v16, 0xff, v16
	s_mov_b64 exec, s[40:41]
	v_lshl_add_u32 v20, v16, 1, v179
	ds_write_b16 v20, v18
	s_mov_b64 exec, s[42:43]
	s_cbranch_execz .Lm6_nb6
	v_ashrrev_i32_e32 v22, 31, v94
	v_sub_u32_e32 v18, 0x1fff, v18
	v_lshl_add_u32 v20, v16, 2, v169
	v_bitop3_b32 v21, v22, v94, s64 bitop3:0x36
	v_and_or_b32 v21, v21, s65, v18
	ds_write_b32 v20, v21
.Lm6_nb6:
	s_mov_b64 exec, -1
	v_cmp_ge_f32_e64 s[40:41], v96, v122
	v_cmp_ge_f32_e64 s[42:43], v96, v123
	v_or_b32_e32 v18, 16, v124
	s_andn2_b64 s[42:43], s[42:43], s[40:41]
	s_mov_b64 exec, s[40:41]
	ds_add_rtn_u32 v16, v180, v222
	s_mov_b64 exec, s[42:43]
	ds_add_rtn_u32 v16, v171, v222
	s_mov_b64 exec, -1
	s_waitcnt lgkmcnt(3)
	v_and_b32_e32 v17, 0xff, v17
	s_mov_b64 exec, s[44:45]
	v_lshl_add_u32 v20, v17, 1, v179
	ds_write_b16 v20, v19
	s_mov_b64 exec, s[22:23]
	s_cbranch_execz .Lm6_nb7
	v_ashrrev_i32_e32 v22, 31, v95
	v_sub_u32_e32 v19, 0x1fff, v19
	v_lshl_add_u32 v20, v17, 2, v169
	v_bitop3_b32 v21, v22, v95, s64 bitop3:0x36
	v_and_or_b32 v21, v21, s65, v19
	ds_write_b32 v20, v21
.Lm6_nb7:
	s_mov_b64 exec, -1
	v_cmp_ge_f32_e64 s[44:45], v97, v122
	v_cmp_ge_f32_e64 s[22:23], v97, v123
	v_or_b32_e32 v19, 17, v124
	s_andn2_b64 s[22:23], s[22:23], s[44:45]
	s_mov_b64 exec, s[44:45]
	ds_add_rtn_u32 v17, v180, v222
	s_mov_b64 exec, s[22:23]
	ds_add_rtn_u32 v17, v171, v222
	s_mov_b64 exec, -1
	s_waitcnt lgkmcnt(3)
	v_and_b32_e32 v16, 0xff, v16
	s_mov_b64 exec, s[40:41]
	v_lshl_add_u32 v20, v16, 1, v179
	ds_write_b16 v20, v18
	s_mov_b64 exec, s[42:43]
	s_cbranch_execz .Lm6_nb8
	v_ashrrev_i32_e32 v22, 31, v96
	v_sub_u32_e32 v18, 0x1fff, v18
	v_lshl_add_u32 v20, v16, 2, v169
	v_bitop3_b32 v21, v22, v96, s64 bitop3:0x36
	v_and_or_b32 v21, v21, s65, v18
	ds_write_b32 v20, v21
;     ...
;         const unsigned s0 = (unsigned)(64 * kt + 32 * kb + 4 * hi);
; #pragma unroll
;         for (int r = 0; r < 16; ++r) { const unsigned s = s0 + (unsigned)((r & 3) + 8 * (r >> 2));
;             if (MODE == 5) { __hip_atomic_fetch_add(hist + 64 * bucketf(sc[r]), 1u, __ATOMIC_RELAXED, __HIP_MEMORY_SCOPE_WORKGROUP); continue; }
;             if (MODE == 6) {
;                 if (sc[r] >= t_hi) { const unsigned pos = __hip_atomic_fetch_add(cnt, 1u, __ATOMIC_RELAXED, __HIP_MEMORY_SCOPE_WORKGROUP); sel[pos & 255u] = (unsigned short)s; }
;                 else if (sc[r] >= t_lo) { const unsigned key = (sortable(sc[r]) & 0xFFFFE000u) | (8191u - s);
;                     const unsigned pos = __hip_atomic_fetch_add(ccnt, 1u, __ATOMIC_RELAXED, __HIP_MEMORY_SCOPE_WORKGROUP); cand[pos & (DS_CAP - 1)] = key; }
;                 continue; }
;             if (MODE == 7) { if (bucketf(sc[r]) == (int)pref) { const unsigned key = (sortable(sc[r]) & 0xFFFFE000u) | (8191u - s);
;                     __hip_atomic_fetch_add(hist + 64 * ((key >> 12) & 255u), 1u, __ATOMIC_RELAXED, __HIP_MEMORY_SCOPE_WORKGROUP); } continue; }
;             if (MODE == 8) { const int dA = bucketf(sc[r]);
;                 if (dA > (int)pref) { const unsigned pos = __hip_atomic_fetch_add(cnt, 1u, __ATOMIC_RELAXED, __HIP_MEMORY_SCOPE_WORKGROUP); sel[pos & 255u] = (unsigned short)s; }
;                 else if (dA == (int)pref) { const unsigned key = (sortable(sc[r]) & 0xFFFFE000u) | (8191u - s); const unsigned sub = (key >> 12) & 255u;
;                     if (sub > pref2) { const unsigned pos = __hip_atomic_fetch_add(cnt, 1u, __ATOMIC_RELAXED, __HIP_MEMORY_SCOPE_WORKGROUP); sel[pos & 255u] = (unsigned short)s; }
;                     else if (sub == pref2) { const unsigned pos = __hip_atomic_fetch_add(ccnt, 1u, __ATOMIC_RELAXED, __HIP_MEMORY_SCOPE_WORKGROUP); cand[pos & (DS_CAP - 1)] = key; } }
;                 continue; }
;             const unsigned key = (sortable(sc[r]) & 0xFFFFE000u) | (8191u - s);
;             if (MODE < 4) { bool ok = true; if (SHIFT < 24) ok = (key >> ((SHIFT + 8) & 31)) == pref;
;                 if (ok) __hip_atomic_fetch_add(hist + 64 * ((key >> (SHIFT & 31)) & 255u), 1u, __ATOMIC_RELAXED, __HIP_MEMORY_SCOPE_WORKGROUP); }
.Lm6_nb8:
	s_mov_b64 exec, -1
	v_cmp_ge_f32_e64 s[40:41], v98, v122
	v_cmp_ge_f32_e64 s[42:43], v98, v123
	v_or_b32_e32 v18, 18, v124
	s_andn2_b64 s[42:43], s[42:43], s[40:41]
	s_mov_b64 exec, s[40:41]
	ds_add_rtn_u32 v16, v180, v222
	s_mov_b64 exec, s[42:43]
	ds_add_rtn_u32 v16, v171, v222
	s_mov_b64 exec, -1
	s_waitcnt lgkmcnt(3)
	v_and_b32_e32 v17, 0xff, v17
	s_mov_b64 exec, s[44:45]
	v_lshl_add_u32 v20, v17, 1, v179
	ds_write_b16 v20, v19
	s_mov_b64 exec, s[22:23]
	s_cbranch_execz .Lm6_nb9
	v_ashrrev_i32_e32 v22, 31, v97
	v_sub_u32_e32 v19, 0x1fff, v19
	v_lshl_add_u32 v20, v17, 2, v169
	v_bitop3_b32 v21, v22, v97, s64 bitop3:0x36
	v_and_or_b32 v21, v21, s65, v19
	ds_write_b32 v20, v21
.Lm6_nb9:
	s_mov_b64 exec, -1
	v_cmp_ge_f32_e64 s[44:45], v99, v122
	v_cmp_ge_f32_e64 s[22:23], v99, v123
	v_or_b32_e32 v19, 19, v124
	s_andn2_b64 s[22:23], s[22:23], s[44:45]
	s_mov_b64 exec, s[44:45]
	ds_add_rtn_u32 v17, v180, v222
	s_mov_b64 exec, s[22:23]
	ds_add_rtn_u32 v17, v171, v222
	s_mov_b64 exec, -1
	s_waitcnt lgkmcnt(3)
	v_and_b32_e32 v16, 0xff, v16
	s_mov_b64 exec, s[40:41]
	v_lshl_add_u32 v20, v16, 1, v179
	ds_write_b16 v20, v18
	s_mov_b64 exec, s[42:43]
	s_cbranch_execz .Lm6_nb10
	v_ashrrev_i32_e32 v22, 31, v98
	v_sub_u32_e32 v18, 0x1fff, v18
	v_lshl_add_u32 v20, v16, 2, v169
	v_bitop3_b32 v21, v22, v98, s64 bitop3:0x36
	v_and_or_b32 v21, v21, s65, v18
	ds_write_b32 v20, v21
.Lm6_nb10:
	s_mov_b64 exec, -1
	v_cmp_ge_f32_e64 s[40:41], v100, v122
	v_cmp_ge_f32_e64 s[42:43], v100, v123
	v_or_b32_e32 v18, 24, v124
	s_andn2_b64 s[42:43], s[42:43], s[40:41]
	s_mov_b64 exec, s[40:41]
	ds_add_rtn_u32 v16, v180, v222
	s_mov_b64 exec, s[42:43]
	ds_add_rtn_u32 v16, v171, v222
	s_mov_b64 exec, -1
	s_waitcnt lgkmcnt(3)
	v_and_b32_e32 v17, 0xff, v17
	s_mov_b64 exec, s[44:45]
	v_lshl_add_u32 v20, v17, 1, v179
	ds_write_b16 v20, v19
	s_mov_b64 exec, s[22:23]
	s_cbranch_execz .Lm6_nb11
	v_ashrrev_i32_e32 v22, 31, v99
	v_sub_u32_e32 v19, 0x1fff, v19
	v_lshl_add_u32 v20, v17, 2, v169
	v_bitop3_b32 v21, v22, v99, s64 bitop3:0x36
	v_and_or_b32 v21, v21, s65, v19
	ds_write_b32 v20, v21
.Lm6_nb11:
	s_mov_b64 exec, -1
	v_cmp_ge_f32_e64 s[44:45], v101, v122
	v_cmp_ge_f32_e64 s[22:23], v101, v123
	v_or_b32_e32 v19, 25, v124
	s_andn2_b64 s[22:23], s[22:23], s[44:45]
	s_mov_b64 exec, s[44:45]
	ds_add_rtn_u32 v17, v180, v222
	s_mov_b64 exec, s[22:23]
	ds_add_rtn_u32 v17, v171, v222
	s_mov_b64 exec, -1
	s_waitcnt lgkmcnt(3)
	v_and_b32_e32 v16, 0xff, v16
	s_mov_b64 exec, s[40:41]
	v_lshl_add_u32 v20, v16, 1, v179
	ds_write_b16 v20, v18
	s_mov_b64 exec, s[42:43]
	s_cbranch_execz .Lm6_nb12
	v_ashrrev_i32_e32 v22, 31, v100
	v_sub_u32_e32 v18, 0x1fff, v18
	v_lshl_add_u32 v20, v16, 2, v169
	v_bitop3_b32 v21, v22, v100, s64 bitop3:0x36
	v_and_or_b32 v21, v21, s65, v18
	ds_write_b32 v20, v21
.Lm6_nb12:
	s_mov_b64 exec, -1
	v_cmp_ge_f32_e64 s[40:41], v102, v122
	v_cmp_ge_f32_e64 s[42:43], v102, v123
	v_or_b32_e32 v18, 26, v124
	s_andn2_b64 s[42:43], s[42:43], s[40:41]
	s_mov_b64 exec, s[40:41]
	ds_add_rtn_u32 v16, v180, v222
	s_mov_b64 exec, s[42:43]
	ds_add_rtn_u32 v16, v171, v222
	s_mov_b64 exec, -1
	s_waitcnt lgkmcnt(3)
	v_and_b32_e32 v17, 0xff, v17
	s_mov_b64 exec, s[44:45]
	v_lshl_add_u32 v20, v17, 1, v179
	ds_write_b16 v20, v19
	s_mov_b64 exec, s[22:23]
	s_cbranch_execz .Lm6_nb13
	v_ashrrev_i32_e32 v22, 31, v101
	v_sub_u32_e32 v19, 0x1fff, v19
	v_lshl_add_u32 v20, v17, 2, v169
	v_bitop3_b32 v21, v22, v101, s64 bitop3:0x36
	v_and_or_b32 v21, v21, s65, v19
	ds_write_b32 v20, v21
.Lm6_nb13:
	s_mov_b64 exec, -1
	v_cmp_ge_f32_e64 s[44:45], v103, v122
	v_cmp_ge_f32_e64 s[22:23], v103, v123
	v_or_b32_e32 v19, 27, v124
	s_andn2_b64 s[22:23], s[22:23], s[44:45]
	s_mov_b64 exec, s[44:45]
	ds_add_rtn_u32 v17, v180, v222
	s_mov_b64 exec, s[22:23]
	ds_add_rtn_u32 v17, v171, v222
	s_mov_b64 exec, -1
	s_waitcnt lgkmcnt(3)
	v_and_b32_e32 v16, 0xff, v16
	s_mov_b64 exec, s[40:41]
	v_lshl_add_u32 v20, v16, 1, v179
	ds_write_b16 v20, v18
	s_mov_b64 exec, s[42:43]
	s_cbranch_execz .Lm6_nb14
	v_ashrrev_i32_e32 v22, 31, v102
	v_sub_u32_e32 v18, 0x1fff, v18
	v_lshl_add_u32 v20, v16, 2, v169
	v_bitop3_b32 v21, v22, v102, s64 bitop3:0x36
	v_and_or_b32 v21, v21, s65, v18
	ds_write_b32 v20, v21
.Lm6_nb14:
	s_mov_b64 exec, -1
	s_waitcnt lgkmcnt(1)
	v_and_b32_e32 v17, 0xff, v17
	s_mov_b64 exec, s[44:45]
	v_lshl_add_u32 v20, v17, 1, v179
	ds_write_b16 v20, v19
	s_mov_b64 exec, s[22:23]
	s_cbranch_execz .Lm6_nb15
	v_ashrrev_i32_e32 v22, 31, v103
	v_sub_u32_e32 v19, 0x1fff, v19
	v_lshl_add_u32 v20, v17, 2, v169
	v_bitop3_b32 v21, v22, v103, s64 bitop3:0x36
	v_and_or_b32 v21, v21, s65, v19
	ds_write_b32 v20, v21
.Lm6_nb15:
	s_mov_b64 exec, -1
	s_waitcnt vmcnt(0)
	v_mov_b64_e32 v[132:133], v[64:65]
	v_mov_b64_e32 v[134:135], v[66:67]
	v_mov_b64_e32 v[128:129], v[68:69]
	v_mov_b64_e32 v[130:131], v[70:71]
	s_cmp_lg_u32 s25, s1
	s_mov_b32 s18, s1
	s_cbranch_scc1 .Lm6_loop

; #define LAS __attribute__((address_space(3)))
; __device__ __forceinline__ float ex2(float v) { return __builtin_amdgcn_exp2f(v); }
; __device__ __forceinline__ int crow(int r, int hi) { return (r & 3) + 8 * (r >> 2) + 4 * hi; }
; __device__ __forceinline__ f32x16 mfma32(bf16x8 a, bf16x8 b, f32x16 c) { return __builtin_amdgcn_mfma_f32_32x32x16_bf16(a, b, c, 0, 0, 0); }
; __device__ __forceinline__ void fox_tile(LAS const unsigned char* Kb, LAS const unsigned char* Vb, LAS const float* Fb, LAS float* wsf, const bf16x8 (&qr)[4], float Fq, int kt, int kt_my_last, int qw, ...
;     ...
;             for (int g4 = 0; g4 < 4; ++g4) { const f32x4 fa = *(LAS const f32x4*)(Fb + 8 * g4 + 4 * hi), fb = *(LAS const f32x4*)(Fb + 32 + 8 * g4 + 4 * hi);
; #pragma unroll
;                 for (int i = 0; i < 4; ++i) { p0[4 * g4 + i] = fa[i]; p1[4 * g4 + i] = fb[i]; } }
; #pragma unroll
;             for (int d0 = 0; d0 < 4; ++d0) { const bf16x8 a0 = *(LAS const bf16x8*)(Kb + r32 * KST + (d0 * 16 + hi * 8) * 2), a1 = *(LAS const bf16x8*)(Kb + (32 + r32) * KST + (d0 * 16 + hi * 8) * 2);
;                 p0 = mfma32(a0, qr[d0], p0); p1 = mfma32(a1, qr[d0], p1); }
;             if (kt == kt_my_last) { const int qrel = qw + r32 - kt * 64;
; #pragma unroll
;                 for (int r = 0; r < 16; ++r) { const int kv = crow(r, hi); if (kv > qrel) p0[r] = -INFINITY; if (kv + 32 > qrel) p1[r] = -INFINITY; } }
;             float rm = fmaxf(p0[0], p1[0]);
; #pragma unroll
;             for (int r = 1; r < 16; ++r) rm = fmaxf(rm, fmaxf(p0[r], p1[r]));
;             rm = fmaxf(rm, __shfl_xor(rm, 32));
;             if (__any(rm > m_run)) {
;                 const float mn = fmaxf(m_run, rm); const float alpha = ex2(m_run - mn); m_run = mn; l_run *= alpha;
;                 if (hi == 0) wsf[r32] = alpha;
; #pragma unroll
;                 for (int g4 = 0; g4 < 4; ++g4) { const f32x4 al = *(LAS const f32x4*)(wsf + 8 * g4 + 4 * hi);
; #pragma unroll
;                     for (int i = 0; i < 4; ++i) { o0[4 * g4 + i] *= al[i]; o1[4 * g4 + i] *= al[i]; } } }
.LBB0_1861:
	s_and_b32 s9, s8, 1
	s_xor_b32 s88, s9, 1
	s_add_i32 s89, s86, s87
	s_add_i32 s78, s87, 1
	s_cmp_ge_i32 s78, s97
	s_cselect_b64 vcc, -1, 0
	s_cmp_lt_i32 s87, s84
	s_cselect_b64 s[94:95], -1, 0
	s_and_b64 s[94:95], vcc, s[94:95]
	s_mul_i32 s78, s88, 0x4800
	s_andn2_b64 vcc, exec, s[94:95]
	v_lshl_add_u32 v166, s88, 9, v147
	v_add_u32_e32 v165, s78, v148
	s_cbranch_vccnz .LBB0_1868
	ds_read_b128 v[54:57], v165 offset:9216
	ds_read_b128 v[34:37], v166 offset:256
	ds_read_b128 v[38:41], v166 offset:288
	ds_read_b128 v[42:45], v166 offset:320
	ds_read_b128 v[46:49], v166 offset:352
	ds_read_b128 v[168:171], v165 offset:13824
	ds_read_b128 v[50:53], v166 offset:384
	s_cmp_lg_u32 s89, -1
	s_waitcnt lgkmcnt(2)
	v_mfma_f32_32x32x16_bf16 v[34:49], v[54:57], v[82:85], v[34:49]
	ds_read_b128 v[54:57], v166 offset:416
	ds_read_b128 v[58:61], v166 offset:448
	ds_read_b128 v[62:65], v166 offset:480
	ds_read_b128 v[188:191], v165 offset:9248
	ds_read_b128 v[192:195], v165 offset:13856
	ds_read_b128 v[196:199], v165 offset:9280
	ds_read_b128 v[200:203], v165 offset:13888
	ds_read_b128 v[204:207], v165 offset:9312
	ds_read_b128 v[208:211], v165 offset:13920
	s_waitcnt lgkmcnt(6)
	v_mfma_f32_32x32x16_bf16 v[50:65], v[168:171], v[82:85], v[50:65]
	s_waitcnt lgkmcnt(5)
	v_mfma_f32_32x32x16_bf16 v[34:49], v[188:191], v[86:89], v[34:49]
	s_waitcnt lgkmcnt(4)
	v_mfma_f32_32x32x16_bf16 v[50:65], v[192:195], v[86:89], v[50:65]
	s_waitcnt lgkmcnt(3)
	v_mfma_f32_32x32x16_bf16 v[34:49], v[196:199], v[90:93], v[34:49]
	s_waitcnt lgkmcnt(2)
	v_mfma_f32_32x32x16_bf16 v[50:65], v[200:203], v[90:93], v[50:65]
	s_waitcnt lgkmcnt(1)
	v_mfma_f32_32x32x16_bf16 v[34:49], v[204:207], v[94:97], v[34:49]
	s_waitcnt lgkmcnt(0)
	v_mfma_f32_32x32x16_bf16 v[50:65], v[208:211], v[94:97], v[50:65]
	s_cbranch_scc1 .LBB0_1864
	s_nop 8
	v_cndmask_b32_e64 v0, v34, v158, s[10:11]
	s_nop 1
	v_cndmask_b32_e64 v50, v50, v158, s[12:13]
	v_cndmask_b32_e64 v35, v158, v35, s[14:15]
	v_cndmask_b32_e64 v34, v0, v34, s[14:15]
	v_cndmask_b32_e64 v51, v51, v158, s[16:17]
	v_cndmask_b32_e64 v36, v36, v158, s[18:19]
	v_cndmask_b32_e64 v52, v52, v158, s[20:21]
	v_cndmask_b32_e64 v37, v37, v158, s[22:23]
	v_cndmask_b32_e64 v53, v53, v158, s[24:25]
	v_cndmask_b32_e64 v38, v38, v158, s[26:27]
	v_cndmask_b32_e64 v54, v54, v158, s[28:29]
	v_cndmask_b32_e64 v39, v39, v158, s[30:31]
	v_cndmask_b32_e64 v55, v55, v158, s[34:35]
	v_cndmask_b32_e64 v40, v40, v158, s[36:37]
	v_cndmask_b32_e64 v56, v56, v158, s[38:39]
	v_cndmask_b32_e64 v41, v41, v158, s[40:41]
	v_cndmask_b32_e64 v57, v57, v158, s[42:43]
	v_cndmask_b32_e64 v42, v42, v158, s[44:45]
	v_cndmask_b32_e64 v58, v58, v158, s[46:47]
	v_cndmask_b32_e64 v43, v43, v158, s[48:49]
	v_cndmask_b32_e64 v59, v59, v158, s[50:51]
	v_cndmask_b32_e64 v44, v44, v158, s[52:53]
	v_cndmask_b32_e64 v60, v60, v158, s[54:55]
	v_cndmask_b32_e64 v45, v45, v158, s[56:57]
	v_cndmask_b32_e64 v61, v61, v158, s[58:59]
	v_cndmask_b32_e64 v46, v46, v158, s[60:61]
	v_cndmask_b32_e64 v62, v62, v158, s[62:63]
	v_cndmask_b32_e64 v47, v47, v158, s[64:65]
	v_cndmask_b32_e64 v63, v63, v158, s[66:67]
	v_cndmask_b32_e64 v48, v48, v158, s[68:69]
	v_cndmask_b32_e64 v64, v64, v158, s[70:71]
	v_cndmask_b32_e64 v49, v49, v158, s[72:73]
	v_cndmask_b32_e64 v65, v65, v158, s[74:75]
.LBB0_1864:
	s_nop 10
	v_max_f32_e32 v0, v35, v51
	v_max_f32_e32 v167, v36, v52
	v_max3_f32 v0, v34, v50, v0
	v_max_f32_e32 v168, v37, v53
	v_max3_f32 v0, v0, v167, v168
	v_max_f32_e32 v167, v38, v54
	v_max_f32_e32 v168, v39, v55
	v_max3_f32 v0, v0, v167, v168
	v_max_f32_e32 v167, v40, v56
	v_max_f32_e32 v168, v41, v57
	v_max3_f32 v0, v0, v167, v168
	v_max_f32_e32 v167, v42, v58
	v_max_f32_e32 v168, v43, v59
	v_max3_f32 v0, v0, v167, v168
	v_max_f32_e32 v167, v44, v60
	v_max_f32_e32 v168, v45, v61
	v_max3_f32 v0, v0, v167, v168
	v_max_f32_e32 v167, v46, v62
	v_max_f32_e32 v168, v47, v63
	v_max3_f32 v0, v0, v167, v168
	v_max_f32_e32 v167, v48, v64
	v_max_f32_e32 v168, v49, v65
	v_max3_f32 v0, v0, v167, v168
	ds_bpermute_b32 v167, v109, v0
	s_waitcnt lgkmcnt(0)
	v_max_f32_e32 v0, v0, v167
	v_cmp_gt_f32_e32 vcc, v0, v164
	s_cbranch_vccz .LBB0_1869
	v_max_f32_e32 v167, v164, v0
	v_sub_f32_e32 v0, v164, v167
	v_exp_f32_e32 v0, v0
	s_and_saveexec_b64 vcc, s[4:5]
	ds_write_b32 v161, v0
	s_or_b64 exec, exec, vcc
	v_mul_f32_e32 v162, v162, v0
	v_add_u32_e32 v0, s33, v153
	ds_read_b128 v[168:171], v0
	ds_read_b128 v[172:175], v0 offset:32
	ds_read_b128 v[176:179], v0 offset:64
	ds_read_b128 v[180:183], v0 offset:96
	s_waitcnt lgkmcnt(3)
	v_pk_mul_f32 v[20:21], v[20:21], v[170:171]
	s_waitcnt lgkmcnt(2)
	v_pk_mul_f32 v[22:23], v[22:23], v[172:173]
	s_waitcnt lgkmcnt(1)
	v_pk_mul_f32 v[26:27], v[26:27], v[176:177]
	s_waitcnt lgkmcnt(0)
	v_pk_mul_f32 v[30:31], v[30:31], v[180:181]
	v_pk_mul_f32 v[32:33], v[32:33], v[182:183]
	v_pk_mul_f32 v[28:29], v[28:29], v[178:179]
	v_pk_mul_f32 v[24:25], v[24:25], v[174:175]
	v_pk_mul_f32 v[18:19], v[18:19], v[168:169]
	v_pk_mul_f32 v[14:15], v[14:15], v[180:181]
	v_pk_mul_f32 v[10:11], v[10:11], v[176:177]
	v_pk_mul_f32 v[6:7], v[6:7], v[172:173]
	v_pk_mul_f32 v[16:17], v[16:17], v[182:183]
	v_pk_mul_f32 v[12:13], v[12:13], v[178:179]
	v_pk_mul_f32 v[8:9], v[8:9], v[174:175]
	v_pk_mul_f32 v[4:5], v[4:5], v[170:171]
	v_pk_mul_f32 v[2:3], v[2:3], v[168:169]
	s_branch .LBB0_1870

; #define LAS __attribute__((address_space(3)))
; __device__ __forceinline__ float ex2(float v) { return __builtin_amdgcn_exp2f(v); }
; __device__ __forceinline__ int crow(int r, int hi) { return (r & 3) + 8 * (r >> 2) + 4 * hi; }
; __device__ __forceinline__ f32x16 mfma32(bf16x8 a, bf16x8 b, f32x16 c) { return __builtin_amdgcn_mfma_f32_32x32x16_bf16(a, b, c, 0, 0, 0); }
; __device__ __forceinline__ void fox_tile(LAS const unsigned char* Kb, LAS const unsigned char* Vb, LAS const float* Fb, LAS float* wsf, const bf16x8 (&qr)[4], float Fq, int kt, int kt_my_last, int qw, ...
;     ...
;             for (int g4 = 0; g4 < 4; ++g4) { const f32x4 fa = *(LAS const f32x4*)(Fb + 8 * g4 + 4 * hi), fb = *(LAS const f32x4*)(Fb + 32 + 8 * g4 + 4 * hi);
; #pragma unroll
;                 for (int i = 0; i < 4; ++i) { p0[4 * g4 + i] = fa[i]; p1[4 * g4 + i] = fb[i]; } }
; #pragma unroll
;             for (int d0 = 0; d0 < 4; ++d0) { const bf16x8 a0 = *(LAS const bf16x8*)(Kb + r32 * KST + (d0 * 16 + hi * 8) * 2), a1 = *(LAS const bf16x8*)(Kb + (32 + r32) * KST + (d0 * 16 + hi * 8) * 2);
;                 p0 = mfma32(a0, qr[d0], p0); p1 = mfma32(a1, qr[d0], p1); }
;             if (kt == kt_my_last) { const int qrel = qw + r32 - kt * 64;
; #pragma unroll
;                 for (int r = 0; r < 16; ++r) { const int kv = crow(r, hi); if (kv > qrel) p0[r] = -INFINITY; if (kv + 32 > qrel) p1[r] = -INFINITY; } }
;             float rm = fmaxf(p0[0], p1[0]);
; #pragma unroll
;             for (int r = 1; r < 16; ++r) rm = fmaxf(rm, fmaxf(p0[r], p1[r]));
;             rm = fmaxf(rm, __shfl_xor(rm, 32));
;             if (__any(rm > m_run)) {
;                 const float mn = fmaxf(m_run, rm); const float alpha = ex2(m_run - mn); m_run = mn; l_run *= alpha;
;                 if (hi == 0) wsf[r32] = alpha;
; #pragma unroll
;                 for (int g4 = 0; g4 < 4; ++g4) { const f32x4 al = *(LAS const f32x4*)(wsf + 8 * g4 + 4 * hi);
; #pragma unroll
;                     for (int i = 0; i < 4; ++i) { o0[4 * g4 + i] *= al[i]; o1[4 * g4 + i] *= al[i]; } } }
.LBB0_1871:
	s_cmp_lt_i32 s87, s97
	s_cselect_b64 s[94:95], -1, 0
	s_cmp_gt_i32 s87, s84
	s_cselect_b64 vcc, -1, 0
	s_or_b64 s[94:95], s[94:95], vcc
	s_and_b64 vcc, exec, s[94:95]
	s_cbranch_vccnz .LBB0_1878
	ds_read_b128 v[54:57], v165
	ds_read_b128 v[34:37], v166
	ds_read_b128 v[38:41], v166 offset:32
	ds_read_b128 v[42:45], v166 offset:64
	ds_read_b128 v[46:49], v166 offset:96
	ds_read_b128 v[168:171], v165 offset:4608
	ds_read_b128 v[50:53], v166 offset:128
	s_cmp_lg_u32 s89, 0
	s_waitcnt lgkmcnt(2)
	v_mfma_f32_32x32x16_bf16 v[34:49], v[54:57], v[82:85], v[34:49]
	ds_read_b128 v[54:57], v166 offset:160
	ds_read_b128 v[58:61], v166 offset:192
	ds_read_b128 v[62:65], v166 offset:224
	ds_read_b128 v[188:191], v165 offset:32
	ds_read_b128 v[192:195], v165 offset:4640
	ds_read_b128 v[196:199], v165 offset:64
	ds_read_b128 v[200:203], v165 offset:4672
	ds_read_b128 v[204:207], v165 offset:96
	ds_read_b128 v[208:211], v165 offset:4704
	s_waitcnt lgkmcnt(6)
	v_mfma_f32_32x32x16_bf16 v[50:65], v[168:171], v[82:85], v[50:65]
	s_waitcnt lgkmcnt(5)
	v_mfma_f32_32x32x16_bf16 v[34:49], v[188:191], v[86:89], v[34:49]
	s_waitcnt lgkmcnt(4)
	v_mfma_f32_32x32x16_bf16 v[50:65], v[192:195], v[86:89], v[50:65]
	s_waitcnt lgkmcnt(3)
	v_mfma_f32_32x32x16_bf16 v[34:49], v[196:199], v[90:93], v[34:49]
	s_waitcnt lgkmcnt(2)
	v_mfma_f32_32x32x16_bf16 v[50:65], v[200:203], v[90:93], v[50:65]
	s_waitcnt lgkmcnt(1)
	v_mfma_f32_32x32x16_bf16 v[34:49], v[204:207], v[94:97], v[34:49]
	s_waitcnt lgkmcnt(0)
	v_mfma_f32_32x32x16_bf16 v[50:65], v[208:211], v[94:97], v[50:65]
	s_cbranch_scc1 .LBB0_1874
	v_cmp_le_i32_e32 vcc, v113, v163
	s_nop 9
	v_cndmask_b32_e32 v50, v158, v50, vcc
	v_cmp_lt_i32_e32 vcc, v159, v163
	s_nop 1
	v_cndmask_b32_e32 v35, v158, v35, vcc
	v_cmp_le_i32_e32 vcc, v159, v163
	s_nop 1
	v_cndmask_b32_e32 v34, v158, v34, vcc
	v_cmp_le_i32_e32 vcc, v114, v163
	s_nop 1
	v_cndmask_b32_e32 v51, v158, v51, vcc
	v_cmp_le_i32_e32 vcc, v115, v163
	s_nop 1
	v_cndmask_b32_e32 v36, v158, v36, vcc
	v_cmp_le_i32_e32 vcc, v116, v163
	s_nop 1
	v_cndmask_b32_e32 v52, v158, v52, vcc
	v_cmp_le_i32_e32 vcc, v117, v163
	s_nop 1
	v_cndmask_b32_e32 v37, v158, v37, vcc
	v_cmp_le_i32_e32 vcc, v118, v163
	s_nop 1
	v_cndmask_b32_e32 v53, v158, v53, vcc
	v_cmp_le_i32_e32 vcc, v119, v163
	s_nop 1
	v_cndmask_b32_e32 v38, v158, v38, vcc
	v_cmp_le_i32_e32 vcc, v120, v163
	s_nop 1
	v_cndmask_b32_e32 v54, v158, v54, vcc
	v_cmp_le_i32_e32 vcc, v121, v163
	s_nop 1
	v_cndmask_b32_e32 v39, v158, v39, vcc
	v_cmp_le_i32_e32 vcc, v122, v163
	s_nop 1
	v_cndmask_b32_e32 v55, v158, v55, vcc
	v_cmp_le_i32_e32 vcc, v123, v163
	s_nop 1
	v_cndmask_b32_e32 v40, v158, v40, vcc
	v_cmp_le_i32_e32 vcc, v124, v163
	s_nop 1
	v_cndmask_b32_e32 v56, v158, v56, vcc
	v_cmp_le_i32_e32 vcc, v125, v163
	s_nop 1
	v_cndmask_b32_e32 v41, v158, v41, vcc
	v_cmp_le_i32_e32 vcc, v126, v163
	s_nop 1
	v_cndmask_b32_e32 v57, v158, v57, vcc
	v_cmp_le_i32_e32 vcc, v127, v163
	s_nop 1
	v_cndmask_b32_e32 v42, v158, v42, vcc
	v_cmp_le_i32_e32 vcc, v128, v163
	s_nop 1
	v_cndmask_b32_e32 v58, v158, v58, vcc
	v_cmp_le_i32_e32 vcc, v129, v163
	s_nop 1
	v_cndmask_b32_e32 v43, v158, v43, vcc
	v_cmp_le_i32_e32 vcc, v130, v163
	s_nop 1
	v_cndmask_b32_e32 v59, v158, v59, vcc
	v_cmp_le_i32_e32 vcc, v131, v163
	s_nop 1
	v_cndmask_b32_e32 v44, v158, v44, vcc
	v_cmp_le_i32_e32 vcc, v132, v163
	s_nop 1
	v_cndmask_b32_e32 v60, v158, v60, vcc
	v_cmp_le_i32_e32 vcc, v133, v163
	s_nop 1
	v_cndmask_b32_e32 v45, v158, v45, vcc
	v_cmp_le_i32_e32 vcc, v134, v163
	s_nop 1
	v_cndmask_b32_e32 v61, v158, v61, vcc
	v_cmp_le_i32_e32 vcc, v135, v163
	s_nop 1
	v_cndmask_b32_e32 v46, v158, v46, vcc
	v_cmp_le_i32_e32 vcc, v136, v163
	s_nop 1
	v_cndmask_b32_e32 v62, v158, v62, vcc
	v_cmp_le_i32_e32 vcc, v137, v163
	s_nop 1
	v_cndmask_b32_e32 v47, v158, v47, vcc
	v_cmp_le_i32_e32 vcc, v138, v163
	s_nop 1
	v_cndmask_b32_e32 v63, v158, v63, vcc
	v_cmp_le_i32_e32 vcc, v139, v163
	s_nop 1
	v_cndmask_b32_e32 v48, v158, v48, vcc
	v_cmp_le_i32_e32 vcc, v140, v163
	s_nop 1
	v_cndmask_b32_e32 v64, v158, v64, vcc
	v_cmp_le_i32_e32 vcc, v141, v163
	s_nop 1
	v_cndmask_b32_e32 v49, v158, v49, vcc
	v_cmp_le_i32_e32 vcc, v142, v163
	s_nop 1
	v_cndmask_b32_e32 v65, v158, v65, vcc
.LBB0_1874:
	s_nop 10
	v_max_f32_e32 v0, v35, v51
	v_max_f32_e32 v164, v36, v52
	v_max3_f32 v0, v34, v50, v0
	v_max_f32_e32 v165, v37, v53
	v_max3_f32 v0, v0, v164, v165
	v_max_f32_e32 v164, v38, v54
	v_max_f32_e32 v165, v39, v55
	v_max3_f32 v0, v0, v164, v165
	v_max_f32_e32 v164, v40, v56
	v_max_f32_e32 v165, v41, v57
	v_max3_f32 v0, v0, v164, v165
	v_max_f32_e32 v164, v42, v58
	v_max_f32_e32 v165, v43, v59
	v_max3_f32 v0, v0, v164, v165
	v_max_f32_e32 v164, v44, v60
	v_max_f32_e32 v165, v45, v61
	v_max3_f32 v0, v0, v164, v165
	v_max_f32_e32 v164, v46, v62
	v_max_f32_e32 v165, v47, v63
	v_max3_f32 v0, v0, v164, v165
	v_max_f32_e32 v164, v48, v64
	v_max_f32_e32 v165, v49, v65
	v_max3_f32 v0, v0, v164, v165
	ds_bpermute_b32 v164, v109, v0
	s_waitcnt lgkmcnt(0)
	v_max_f32_e32 v0, v0, v164
	v_cmp_gt_f32_e32 vcc, v0, v167
	s_cbranch_vccz .LBB0_1879
	v_max_f32_e32 v164, v167, v0
	v_sub_f32_e32 v0, v167, v164
	v_exp_f32_e32 v0, v0
	s_and_saveexec_b64 vcc, s[4:5]
	ds_write_b32 v161, v0
	s_or_b64 exec, exec, vcc
	v_mul_f32_e32 v162, v162, v0
	v_add_u32_e32 v0, s33, v153
	ds_read_b128 v[166:169], v0
	ds_read_b128 v[170:173], v0 offset:32
	ds_read_b128 v[174:177], v0 offset:64
	ds_read_b128 v[178:181], v0 offset:96
	s_waitcnt lgkmcnt(3)
	v_pk_mul_f32 v[20:21], v[20:21], v[168:169]
	s_waitcnt lgkmcnt(2)
	v_pk_mul_f32 v[22:23], v[22:23], v[170:171]
	s_waitcnt lgkmcnt(1)
	v_pk_mul_f32 v[26:27], v[26:27], v[174:175]
	s_waitcnt lgkmcnt(0)
	v_pk_mul_f32 v[30:31], v[30:31], v[178:179]
	v_pk_mul_f32 v[32:33], v[32:33], v[180:181]
	v_pk_mul_f32 v[28:29], v[28:29], v[176:177]
	v_pk_mul_f32 v[24:25], v[24:25], v[172:173]
	v_pk_mul_f32 v[18:19], v[18:19], v[166:167]
	v_pk_mul_f32 v[14:15], v[14:15], v[178:179]
	v_pk_mul_f32 v[10:11], v[10:11], v[174:175]
	v_pk_mul_f32 v[6:7], v[6:7], v[170:171]
	v_pk_mul_f32 v[16:17], v[16:17], v[180:181]
	v_pk_mul_f32 v[12:13], v[12:13], v[176:177]
	v_pk_mul_f32 v[8:9], v[8:9], v[172:173]
	v_pk_mul_f32 v[4:5], v[4:5], v[168:169]
	v_pk_mul_f32 v[2:3], v[2:3], v[166:167]
	s_branch .LBB0_1880
